# v38 plus MFMA-first ordering in the first unrolled attention step
# speedup vs baseline: 1.0014x; 1.0014x over previous
; #define WAIT_BAR(N) asm volatile("s_waitcnt vmcnt(" #N ") lgkmcnt(0)\n\ts_barrier":::"memory")
;   #define RESC() do{ if(resc){ asm volatile("s_waitcnt lgkmcnt(0)":::"memory"); \
;       _Pragma("unroll") for(int d_=0;d_<2;++d_) _Pragma("unroll") for(int r=0;r<16;++r)o[d_][r]*=wsf[crow(r,hi)]; } }while(0)
;   #define ROT() do{sl_prev=sl_cur;sl_cur=sl_next;sl_next=(sl_next==(NSLOT-1)*SLOTB)?0:sl_next+SLOTB;}while(0)
; template<int THRL> __device__ __forceinline__ void attn_unit(const bf16*Qu,const bf16*__restrict__ Kh,const bf16*__restrict__ Vh,bf16*Ou,const int NT,const float shift,char*shm){
;     ...
;   int t=1;
;     ...
;   for(;t+5<NT;t+=2){
;     STEP(pB0,pB1,pA0,pA1,t,true,true,true);     WAIT_BAR(2); RESC(); ROT();
.LBB0_618:
	s_mov_b32 s4, s76
	s_mov_b32 s5, s26
	s_mov_b32 s25, s31
	v_add_u32_e32 v51, s24, v245
	ds_read_b64_tr_b16 v[52:53], v51 offset:24576
	ds_read_b64_tr_b16 v[54:55], v51 offset:25088
	s_waitcnt lgkmcnt(9)
	v_mfma_f32_32x32x16_bf16 v[114:129], v[190:193], v[150:153], v[34:49]
	v_add_f32_e32 v50, v82, v50
	v_add_f32_e32 v194, v83, v194
	v_add_f32_e32 v195, v84, v195
	v_add_f32_e32 v196, v85, v196
	v_add_f32_e32 v50, v86, v50
	v_add_f32_e32 v194, v87, v194
	v_cvt_pk_bf16_f32 v158, v82, v83
	v_cvt_pk_bf16_f32 v159, v84, v85
	ds_read_b64_tr_b16 v[60:61], v51 offset:28672
	ds_read_b64_tr_b16 v[62:63], v51 offset:29184
	s_waitcnt lgkmcnt(10)
	v_mfma_f32_32x32x16_bf16 v[98:113], v[186:189], v[150:153], v[34:49]
	v_add_f32_e32 v195, v88, v195
	v_add_f32_e32 v196, v89, v196
	v_add_f32_e32 v50, v90, v50
	v_add_f32_e32 v194, v91, v194
	v_cvt_pk_bf16_f32 v160, v86, v87
	v_cvt_pk_bf16_f32 v161, v88, v89
	ds_read_b64_tr_b16 v[82:83], v51 offset:25600
	ds_read_b64_tr_b16 v[84:85], v51 offset:26112
	s_waitcnt lgkmcnt(11)
	v_mfma_f32_32x32x16_bf16 v[114:129], v[182:185], v[138:141], v[114:129]
	v_add_f32_e32 v195, v92, v195
	v_add_f32_e32 v196, v93, v196
	v_add_f32_e32 v50, v94, v50
	v_add_f32_e32 v194, v95, v194
	v_cvt_pk_bf16_f32 v154, v90, v91
	v_cvt_pk_bf16_f32 v155, v92, v93
	ds_read_b64_tr_b16 v[86:87], v51 offset:29696
	ds_read_b64_tr_b16 v[88:89], v51 offset:30208
	s_waitcnt lgkmcnt(12)
	v_mfma_f32_32x32x16_bf16 v[98:113], v[178:181], v[138:141], v[98:113]
	v_add_f32_e32 v195, v96, v195
	v_add_f32_e32 v196, v97, v196
	v_add_f32_e32 v50, v66, v50
	v_add_f32_e32 v194, v67, v194
	v_cvt_pk_bf16_f32 v156, v94, v95
	v_cvt_pk_bf16_f32 v157, v96, v97
	ds_read_b64_tr_b16 v[90:91], v51 offset:26624
	ds_read_b64_tr_b16 v[92:93], v51 offset:27136
	s_waitcnt lgkmcnt(13)
	v_mfma_f32_32x32x16_bf16 v[114:129], v[174:177], v[134:137], v[114:129]
	v_add_f32_e32 v195, v68, v195
	v_add_f32_e32 v196, v69, v196
	v_add_f32_e32 v50, v70, v50
	v_add_f32_e32 v194, v71, v194
	v_cvt_pk_bf16_f32 v146, v66, v67
	v_cvt_pk_bf16_f32 v147, v68, v69
	ds_read_b64_tr_b16 v[64:65], v51 offset:30720
	ds_read_b64_tr_b16 v[66:67], v51 offset:31232
	s_waitcnt lgkmcnt(14)
	v_mfma_f32_32x32x16_bf16 v[98:113], v[170:173], v[134:137], v[98:113]
	v_add_f32_e32 v195, v72, v195
	v_add_f32_e32 v196, v73, v196
	v_add_f32_e32 v50, v74, v50
	v_add_f32_e32 v194, v75, v194
	v_cvt_pk_bf16_f32 v148, v70, v71
	v_cvt_pk_bf16_f32 v149, v72, v73
	ds_read_b64_tr_b16 v[68:69], v51 offset:27648
	ds_read_b64_tr_b16 v[70:71], v51 offset:28160
	s_waitcnt lgkmcnt(14)
	v_mfma_f32_32x32x16_bf16 v[114:129], v[166:169], v[130:133], v[114:129]
	v_add_f32_e32 v195, v76, v195
	v_add_f32_e32 v196, v77, v196
	v_add_f32_e32 v50, v78, v50
	v_add_f32_e32 v194, v79, v194
	v_cvt_pk_bf16_f32 v142, v74, v75
	v_cvt_pk_bf16_f32 v143, v76, v77
	ds_read_b64_tr_b16 v[72:73], v51 offset:31744
	ds_read_b64_tr_b16 v[74:75], v51 offset:32256
	v_mfma_f32_32x32x16_bf16 v[98:113], v[162:165], v[130:133], v[98:113]
	v_add_f32_e32 v195, v80, v195
	v_add_f32_e32 v196, v81, v196
	v_cvt_pk_bf16_f32 v144, v78, v79
	v_cvt_pk_bf16_f32 v145, v80, v81
	s_add_i32 s6, s31, s70
	s_mov_b32 s7, m0
	s_mov_b32 m0, s6
	s_nop 0
	global_load_lds_dwordx4 v197, s[98:99]
	s_mov_b32 m0, s7
	s_add_i32 s6, s76, s71
	s_mov_b32 s7, m0
	s_mov_b32 m0, s6
	s_nop 0
	global_load_lds_dwordx4 v197, s[100:101]
	s_mov_b32 m0, s7
	s_add_u32 s98, s98, 0x2000
	s_addc_u32 s99, s99, 0
	s_add_u32 s100, s100, 0x2000
	s_addc_u32 s101, s101, 0
	s_waitcnt lgkmcnt(14)
	v_mfma_f32_32x32x16_bf16 v[2:17], v[158:161], v[52:55], v[2:17]
	v_exp_f32_e32 v114, v114
	v_exp_f32_e32 v115, v115
	v_exp_f32_e32 v116, v116
	v_exp_f32_e32 v117, v117
	s_waitcnt lgkmcnt(12)
	v_mfma_f32_32x32x16_bf16 v[18:33], v[158:161], v[60:63], v[18:33]
	v_exp_f32_e32 v118, v118
	v_exp_f32_e32 v119, v119
	v_exp_f32_e32 v120, v120
	v_exp_f32_e32 v121, v121
	v_add_u32_e32 v52, s4, v244
	ds_read_b128 v[60:63], v52
	ds_read_b128 v[162:165], v52 offset:512
	s_waitcnt lgkmcnt(12)
	v_mfma_f32_32x32x16_bf16 v[2:17], v[154:157], v[82:85], v[2:17]
	v_exp_f32_e32 v122, v122
	v_exp_f32_e32 v123, v123
	v_exp_f32_e32 v124, v124
	v_exp_f32_e32 v125, v125
	ds_read_b128 v[166:169], v52 offset:2048
	ds_read_b128 v[170:173], v52 offset:2560
	s_waitcnt lgkmcnt(12)
	v_mfma_f32_32x32x16_bf16 v[18:33], v[154:157], v[86:89], v[18:33]
	v_exp_f32_e32 v126, v126
	v_exp_f32_e32 v127, v127
	v_exp_f32_e32 v128, v128
	v_exp_f32_e32 v129, v129
	ds_read_b128 v[174:177], v52 offset:4096
	ds_read_b128 v[178:181], v52 offset:4608
	s_waitcnt lgkmcnt(12)
	v_mfma_f32_32x32x16_bf16 v[2:17], v[146:149], v[90:93], v[2:17]
	v_exp_f32_e32 v98, v98
	v_exp_f32_e32 v99, v99
	v_exp_f32_e32 v100, v100
	v_exp_f32_e32 v101, v101
	ds_read_b128 v[182:185], v52 offset:6144
	ds_read_b128 v[52:55], v52 offset:6656
	s_waitcnt lgkmcnt(12)
	v_mfma_f32_32x32x16_bf16 v[18:33], v[146:149], v[64:67], v[18:33]
	v_exp_f32_e32 v102, v102
	v_exp_f32_e32 v103, v103
	v_exp_f32_e32 v104, v104
	v_exp_f32_e32 v105, v105
	s_waitcnt lgkmcnt(10)
	v_mfma_f32_32x32x16_bf16 v[2:17], v[142:145], v[68:71], v[2:17]
	v_exp_f32_e32 v106, v106
	v_exp_f32_e32 v107, v107
	v_exp_f32_e32 v108, v108
	v_exp_f32_e32 v109, v109
	s_waitcnt lgkmcnt(8)
	v_mfma_f32_32x32x16_bf16 v[18:33], v[142:145], v[72:75], v[18:33]
	v_exp_f32_e32 v110, v110
	v_exp_f32_e32 v111, v111
	v_exp_f32_e32 v112, v112
	v_exp_f32_e32 v113, v113
	s_waitcnt vmcnt(2) lgkmcnt(0)
	s_barrier
; #define WAIT_BAR(N) asm volatile("s_waitcnt vmcnt(" #N ") lgkmcnt(0)\n\ts_barrier":::"memory")
;   #define RESC() do{ if(resc){ asm volatile("s_waitcnt lgkmcnt(0)":::"memory"); \
;       _Pragma("unroll") for(int d_=0;d_<2;++d_) _Pragma("unroll") for(int r=0;r<16;++r)o[d_][r]*=wsf[crow(r,hi)]; } }while(0)
;   #define ROT() do{sl_prev=sl_cur;sl_cur=sl_next;sl_next=(sl_next==(NSLOT-1)*SLOTB)?0:sl_next+SLOTB;}while(0)
; template<int THRL> __device__ __forceinline__ void attn_unit(const bf16*Qu,const bf16*__restrict__ Kh,const bf16*__restrict__ Vh,bf16*Ou,const int NT,const float shift,char*shm){
;     ...
;   int t=1;
;     ...
;   for(;t+5<NT;t+=2){
;     STEP(pB0,pB1,pA0,pA1,t,true,true,true);     WAIT_BAR(2); RESC(); ROT();
;     STEP(pA0,pA1,pB0,pB1,t+1,true,true,true);   WAIT_BAR(2); RESC(); ROT();
;   }
	s_add_i32 s6, s76, 0x2000
	s_cmpk_lg_i32 s76, 0x4000
	s_cselect_b32 s31, s6, 0
	v_add_u32_e32 v64, s25, v245
	ds_read_b64_tr_b16 v[186:187], v64 offset:24576
	ds_read_b64_tr_b16 v[188:189], v64 offset:25088
	s_waitcnt lgkmcnt(9)
	v_mfma_f32_32x32x16_bf16 v[82:97], v[60:63], v[150:153], v[34:49]
	v_add_f32_e32 v50, v114, v50
	v_add_f32_e32 v194, v115, v194
	v_add_f32_e32 v195, v116, v195
	v_add_f32_e32 v196, v117, v196
	v_add_f32_e32 v50, v118, v50
	v_add_f32_e32 v194, v119, v194
	v_cvt_pk_bf16_f32 v158, v114, v115
	v_cvt_pk_bf16_f32 v159, v116, v117
	ds_read_b64_tr_b16 v[60:61], v64 offset:28672
	ds_read_b64_tr_b16 v[62:63], v64 offset:29184
	s_waitcnt lgkmcnt(10)
	v_mfma_f32_32x32x16_bf16 v[66:81], v[162:165], v[150:153], v[34:49]
	v_add_f32_e32 v195, v120, v195
	v_add_f32_e32 v196, v121, v196
	v_add_f32_e32 v50, v122, v50
	v_add_f32_e32 v194, v123, v194
	v_cvt_pk_bf16_f32 v160, v118, v119
	v_cvt_pk_bf16_f32 v161, v120, v121
	ds_read_b64_tr_b16 v[114:115], v64 offset:25600
	ds_read_b64_tr_b16 v[116:117], v64 offset:26112
	s_waitcnt lgkmcnt(11)
	v_mfma_f32_32x32x16_bf16 v[82:97], v[166:169], v[138:141], v[82:97]
	v_add_f32_e32 v195, v124, v195
	v_add_f32_e32 v196, v125, v196
	v_add_f32_e32 v50, v126, v50
	v_add_f32_e32 v194, v127, v194
	v_cvt_pk_bf16_f32 v154, v122, v123
	v_cvt_pk_bf16_f32 v155, v124, v125
	ds_read_b64_tr_b16 v[118:119], v64 offset:29696
	ds_read_b64_tr_b16 v[120:121], v64 offset:30208
	s_waitcnt lgkmcnt(12)
	v_mfma_f32_32x32x16_bf16 v[66:81], v[170:173], v[138:141], v[66:81]
	v_add_f32_e32 v195, v128, v195
	v_add_f32_e32 v196, v129, v196
	v_add_f32_e32 v50, v98, v50
	v_add_f32_e32 v194, v99, v194
	v_cvt_pk_bf16_f32 v156, v126, v127
	v_cvt_pk_bf16_f32 v157, v128, v129
	ds_read_b64_tr_b16 v[122:123], v64 offset:26624
	ds_read_b64_tr_b16 v[124:125], v64 offset:27136
	s_waitcnt lgkmcnt(13)
	v_mfma_f32_32x32x16_bf16 v[82:97], v[174:177], v[134:137], v[82:97]
	v_add_f32_e32 v195, v100, v195
	v_add_f32_e32 v196, v101, v196
	v_add_f32_e32 v50, v102, v50
	v_add_f32_e32 v194, v103, v194
	v_cvt_pk_bf16_f32 v146, v98, v99
	v_cvt_pk_bf16_f32 v147, v100, v101
	ds_read_b64_tr_b16 v[98:99], v64 offset:30720
	ds_read_b64_tr_b16 v[100:101], v64 offset:31232
	s_waitcnt lgkmcnt(14)
	v_mfma_f32_32x32x16_bf16 v[66:81], v[178:181], v[134:137], v[66:81]
	v_add_f32_e32 v195, v104, v195
	v_add_f32_e32 v196, v105, v196
	v_add_f32_e32 v50, v106, v50
	v_add_f32_e32 v194, v107, v194
	v_cvt_pk_bf16_f32 v148, v102, v103
	v_cvt_pk_bf16_f32 v149, v104, v105
	ds_read_b64_tr_b16 v[102:103], v64 offset:27648
	ds_read_b64_tr_b16 v[104:105], v64 offset:28160
	s_waitcnt lgkmcnt(14)
	v_mfma_f32_32x32x16_bf16 v[82:97], v[182:185], v[130:133], v[82:97]
	v_add_f32_e32 v195, v108, v195
	v_add_f32_e32 v196, v109, v196
	v_add_f32_e32 v50, v110, v50
	v_add_f32_e32 v194, v111, v194
	v_cvt_pk_bf16_f32 v142, v106, v107
	v_cvt_pk_bf16_f32 v143, v108, v109
	ds_read_b64_tr_b16 v[106:107], v64 offset:31744
	ds_read_b64_tr_b16 v[108:109], v64 offset:32256
	v_mfma_f32_32x32x16_bf16 v[66:81], v[52:55], v[130:133], v[66:81]
	v_add_f32_e32 v195, v112, v195
	v_add_f32_e32 v196, v113, v196
	v_cvt_pk_bf16_f32 v144, v110, v111
	v_cvt_pk_bf16_f32 v145, v112, v113
	s_add_i32 s6, s76, s70
	s_mov_b32 s7, m0
	s_mov_b32 m0, s6
	s_nop 0
	global_load_lds_dwordx4 v197, s[98:99]
	s_mov_b32 m0, s7
	s_add_i32 s6, s31, s71
	s_mov_b32 s7, m0
	s_mov_b32 m0, s6
	s_nop 0
	global_load_lds_dwordx4 v197, s[100:101]
	s_mov_b32 m0, s7
	s_add_u32 s98, s98, 0x2000
	s_addc_u32 s99, s99, 0
	s_add_u32 s100, s100, 0x2000
	s_addc_u32 s101, s101, 0
	s_waitcnt lgkmcnt(14)
	v_mfma_f32_32x32x16_bf16 v[2:17], v[158:161], v[186:189], v[2:17]
	v_exp_f32_e32 v82, v82
	v_exp_f32_e32 v83, v83
	v_exp_f32_e32 v84, v84
	v_exp_f32_e32 v85, v85
	s_waitcnt lgkmcnt(12)
	v_mfma_f32_32x32x16_bf16 v[18:33], v[158:161], v[60:63], v[18:33]
	v_exp_f32_e32 v86, v86
	v_exp_f32_e32 v87, v87
	v_exp_f32_e32 v88, v88
	v_exp_f32_e32 v89, v89
	v_add_u32_e32 v53, s31, v244
	ds_read_b128 v[190:193], v53
	ds_read_b128 v[186:189], v53 offset:512
	s_waitcnt lgkmcnt(12)
	v_mfma_f32_32x32x16_bf16 v[2:17], v[154:157], v[114:117], v[2:17]
	v_exp_f32_e32 v90, v90
	v_exp_f32_e32 v91, v91
	v_exp_f32_e32 v92, v92
	v_exp_f32_e32 v93, v93
	ds_read_b128 v[182:185], v53 offset:2048
	ds_read_b128 v[178:181], v53 offset:2560
	s_waitcnt lgkmcnt(12)
	v_mfma_f32_32x32x16_bf16 v[18:33], v[154:157], v[118:121], v[18:33]
	v_exp_f32_e32 v94, v94
	v_exp_f32_e32 v95, v95
	v_exp_f32_e32 v96, v96
	v_exp_f32_e32 v97, v97
	ds_read_b128 v[174:177], v53 offset:4096
	ds_read_b128 v[170:173], v53 offset:4608
	s_waitcnt lgkmcnt(12)
	v_mfma_f32_32x32x16_bf16 v[2:17], v[146:149], v[122:125], v[2:17]
	v_exp_f32_e32 v66, v66
	v_exp_f32_e32 v67, v67
	v_exp_f32_e32 v68, v68
	v_exp_f32_e32 v69, v69
	ds_read_b128 v[166:169], v53 offset:6144
	ds_read_b128 v[162:165], v53 offset:6656
	s_waitcnt lgkmcnt(12)
	v_mfma_f32_32x32x16_bf16 v[18:33], v[146:149], v[98:101], v[18:33]
	v_exp_f32_e32 v70, v70
	v_exp_f32_e32 v71, v71
	v_exp_f32_e32 v72, v72
	v_exp_f32_e32 v73, v73
	s_waitcnt lgkmcnt(10)
	v_mfma_f32_32x32x16_bf16 v[2:17], v[142:145], v[102:105], v[2:17]
	v_exp_f32_e32 v74, v74
	v_exp_f32_e32 v75, v75
	v_exp_f32_e32 v76, v76
	v_exp_f32_e32 v77, v77
	s_waitcnt lgkmcnt(8)
	v_mfma_f32_32x32x16_bf16 v[18:33], v[142:145], v[106:109], v[18:33]
	v_exp_f32_e32 v78, v78
	v_exp_f32_e32 v79, v79
	v_exp_f32_e32 v80, v80
	v_exp_f32_e32 v81, v81
	s_add_i32 s6, s31, 0x2000
	s_waitcnt vmcnt(2) lgkmcnt(0)
	s_barrier
	s_cmpk_lg_i32 s31, 0x4000
	s_mov_b32 s24, s76
	s_cselect_b32 s76, s6, 0
	s_add_i32 s26, s26, 2
	s_cmp_ge_i32 s26, s91
	s_cbranch_scc0 .LBB0_618
	v_add_f32_e32 v50, v50, v194
	v_add_f32_e32 v50, v50, v195
	v_add_f32_e32 v50, v50, v196
	s_add_i32 s5, s5, -3
	s_branch .LBB0_621
